# k48 + the w_in epilogue stores q/k/v/glu (bf16, re-read by attention and conv) without the non-temporal hint
# speedup vs baseline: 1.0689x; 1.0689x over previous
.LBB0_118:
	v_lshl_add_u32 v144, s66, 7, v167
	s_and_saveexec_b64 s[8:9], s[6:7]
	s_cbranch_execz .LBB0_123
	v_mul_f32_e32 v129, 0xbfb8aa3b, v112
	v_mul_f32_e32 v130, 0xbfb8aa3b, v117
	v_exp_f32_e32 v129, v129
	v_exp_f32_e32 v131, v130
	v_mul_f32_e32 v130, 0xbfb8aa3b, v113
	v_exp_f32_e32 v132, v130
	v_add_f32_e32 v129, 1.0, v129
	v_rcp_f32_e32 v130, v129
	v_add_f32_e32 v129, 1.0, v131
	v_add_f32_e32 v131, 1.0, v132
	v_mul_f32_e32 v132, 0xbfb8aa3b, v118
	v_exp_f32_e32 v132, v132
	v_mul_f32_e32 v133, 0xbfb8aa3b, v114
	v_exp_f32_e32 v133, v133
	v_mul_f32_e32 v128, 0xbfb8aa3b, v116
	v_add_f32_e32 v132, 1.0, v132
	v_rcp_f32_e32 v134, v132
	v_add_f32_e32 v132, 1.0, v133
	v_mul_f32_e32 v133, 0xbfb8aa3b, v119
	v_exp_f32_e32 v133, v133
	v_mul_f32_e32 v135, 0xbfb8aa3b, v115
	v_exp_f32_e32 v128, v128
	v_exp_f32_e32 v157, v135
	v_rcp_f32_e32 v158, v132
	v_add_f32_e32 v132, 1.0, v133
	v_add_f32_e32 v128, 1.0, v128
	v_rcp_f32_e32 v135, v132
	v_add_f32_e32 v132, 1.0, v157
	v_rcp_f32_e32 v128, v128
	v_rcp_f32_e32 v129, v129
	v_rcp_f32_e32 v131, v131
	v_rcp_f32_e32 v159, v132
	v_ashrrev_i32_e32 v157, 31, v156
	v_lshlrev_b64 v[162:163], 10, v[156:157]
	v_lshl_add_u64 v[162:163], s[42:43], 0, v[162:163]
	v_pk_mul_f32 v[132:133], v[128:129], v[124:125]
	v_pk_mul_f32 v[128:129], v[130:131], v[120:121]
	v_pk_mul_f32 v[134:135], v[134:135], v[126:127]
	v_pk_mul_f32 v[130:131], v[158:159], v[122:123]
	v_cvt_pk_bf16_f32 v158, v132, v133
	v_cvt_pk_bf16_f32 v159, v134, v135
	v_lshl_add_u64 v[162:163], v[144:145], 1, v[162:163]
	v_cvt_pk_bf16_f32 v160, v128, v129
	v_cvt_pk_bf16_f32 v161, v130, v131
	global_store_dwordx4 v[162:163], v[158:161], off
	v_cmp_lt_i32_e32 vcc, s77, v156
	s_nop 0
	v_mov_b64_e32 v[158:159], 0
	s_and_saveexec_b64 s[10:11], vcc
	v_add_u32_e32 v157, 0xffffc000, v156
	v_lshrrev_b32_e32 v157, 2, v157
	v_mad_u64_u32 v[158:159], s[64:65], v157, 30, v[146:147]
	v_lshlrev_b64 v[158:159], 11, v[158:159]
	v_lshl_add_u64 v[158:159], s[52:53], 0, v[158:159]
	v_lshl_add_u64 v[158:159], v[144:145], 2, v[158:159]
	s_or_b64 exec, exec, s[10:11]
	v_cmp_ne_u64_e32 vcc, 0, v[158:159]
	s_and_b64 exec, exec, vcc
	s_cbranch_execz .LBB0_123
	global_store_dwordx4 v[158:159], v[132:135], off
	global_store_dwordx4 v[158:159], v[128:131], off offset:16
.LBB0_123:
	s_or_b64 exec, exec, s[8:9]
	v_or_b32_e32 v158, 16, v156
	v_cmp_gt_i32_e32 vcc, s29, v158
	s_and_saveexec_b64 s[8:9], vcc
	s_cbranch_execz .LBB0_128
	v_mul_f32_e32 v129, 0xbfb8aa3b, v96
	v_mul_f32_e32 v130, 0xbfb8aa3b, v101
	v_exp_f32_e32 v129, v129
	v_exp_f32_e32 v131, v130
	v_mul_f32_e32 v130, 0xbfb8aa3b, v97
	v_exp_f32_e32 v132, v130
	v_add_f32_e32 v129, 1.0, v129
	v_rcp_f32_e32 v130, v129
	v_add_f32_e32 v129, 1.0, v131
	v_add_f32_e32 v131, 1.0, v132
	v_mul_f32_e32 v132, 0xbfb8aa3b, v102
	v_exp_f32_e32 v132, v132
	v_mul_f32_e32 v133, 0xbfb8aa3b, v98
	v_exp_f32_e32 v133, v133
	v_mul_f32_e32 v128, 0xbfb8aa3b, v100
	v_add_f32_e32 v132, 1.0, v132
	v_rcp_f32_e32 v134, v132
	v_add_f32_e32 v132, 1.0, v133
	v_mul_f32_e32 v133, 0xbfb8aa3b, v103
	v_exp_f32_e32 v133, v133
	v_mul_f32_e32 v135, 0xbfb8aa3b, v99
	v_exp_f32_e32 v128, v128
	v_exp_f32_e32 v157, v135
	v_rcp_f32_e32 v160, v132
	v_add_f32_e32 v132, 1.0, v133
	v_add_f32_e32 v128, 1.0, v128
	v_rcp_f32_e32 v135, v132
	v_add_f32_e32 v132, 1.0, v157
	v_rcp_f32_e32 v128, v128
	v_rcp_f32_e32 v129, v129
	v_rcp_f32_e32 v131, v131
	v_rcp_f32_e32 v161, v132
	v_ashrrev_i32_e32 v159, 31, v158
	v_lshlrev_b64 v[172:173], 10, v[158:159]
	v_lshl_add_u64 v[172:173], s[42:43], 0, v[172:173]
	v_pk_mul_f32 v[132:133], v[128:129], v[108:109]
	v_pk_mul_f32 v[128:129], v[130:131], v[104:105]
	v_pk_mul_f32 v[134:135], v[134:135], v[110:111]
	v_pk_mul_f32 v[130:131], v[160:161], v[106:107]
	v_lshl_add_u64 v[172:173], v[144:145], 1, v[172:173]
	v_cmp_lt_i32_e32 vcc, s77, v158
	v_mov_b64_e32 v[158:159], 0
	v_cvt_pk_bf16_f32 v160, v132, v133
	v_cvt_pk_bf16_f32 v161, v134, v135
	v_cvt_pk_bf16_f32 v162, v128, v129
	v_cvt_pk_bf16_f32 v163, v130, v131
	global_store_dwordx4 v[172:173], v[160:163], off
	s_and_saveexec_b64 s[10:11], vcc
	v_add_u32_e32 v157, 0xffffc010, v156
	v_lshrrev_b32_e32 v157, 2, v157
	v_mad_u64_u32 v[158:159], s[64:65], v157, 30, v[146:147]
	v_lshlrev_b64 v[158:159], 11, v[158:159]
	v_lshl_add_u64 v[158:159], s[52:53], 0, v[158:159]
	v_lshl_add_u64 v[158:159], v[144:145], 2, v[158:159]
	s_or_b64 exec, exec, s[10:11]
	v_cmp_ne_u64_e32 vcc, 0, v[158:159]
	s_and_b64 exec, exec, vcc
	s_cbranch_execz .LBB0_128
	global_store_dwordx4 v[158:159], v[132:135], off
	global_store_dwordx4 v[158:159], v[128:131], off offset:16
.LBB0_128:
	s_or_b64 exec, exec, s[8:9]
	s_ashr_i32 s8, s24, 11
	s_mul_i32 s8, s8, 30
	v_or_b32_e32 v158, 32, v156
	s_ashr_i32 s9, s8, 31
	v_cmp_gt_i32_e32 vcc, s29, v158
	s_and_saveexec_b64 s[10:11], vcc
	s_cbranch_execz .LBB0_133
	v_mul_f32_e32 v129, 0xbfb8aa3b, v80
	v_mul_f32_e32 v130, 0xbfb8aa3b, v85
	v_exp_f32_e32 v129, v129
	v_exp_f32_e32 v131, v130
	v_mul_f32_e32 v130, 0xbfb8aa3b, v81
	v_exp_f32_e32 v132, v130
	v_add_f32_e32 v129, 1.0, v129
	v_rcp_f32_e32 v130, v129
	v_add_f32_e32 v129, 1.0, v131
	v_add_f32_e32 v131, 1.0, v132
	v_mul_f32_e32 v132, 0xbfb8aa3b, v86
	v_exp_f32_e32 v132, v132
	v_mul_f32_e32 v133, 0xbfb8aa3b, v82
	v_exp_f32_e32 v133, v133
	v_mul_f32_e32 v128, 0xbfb8aa3b, v84
	v_add_f32_e32 v132, 1.0, v132
	v_rcp_f32_e32 v134, v132
	v_add_f32_e32 v132, 1.0, v133
	v_mul_f32_e32 v133, 0xbfb8aa3b, v87
	v_exp_f32_e32 v133, v133
	v_mul_f32_e32 v135, 0xbfb8aa3b, v83
	v_exp_f32_e32 v128, v128
	v_exp_f32_e32 v157, v135
	v_rcp_f32_e32 v160, v132
	v_add_f32_e32 v132, 1.0, v133
	v_add_f32_e32 v128, 1.0, v128
	v_rcp_f32_e32 v135, v132
	v_add_f32_e32 v132, 1.0, v157
	v_rcp_f32_e32 v128, v128
	v_rcp_f32_e32 v129, v129
	v_rcp_f32_e32 v131, v131
	v_rcp_f32_e32 v161, v132
	v_ashrrev_i32_e32 v159, 31, v158
	v_lshlrev_b64 v[172:173], 10, v[158:159]
	v_lshl_add_u64 v[172:173], s[42:43], 0, v[172:173]
	v_pk_mul_f32 v[132:133], v[128:129], v[92:93]
	v_pk_mul_f32 v[128:129], v[130:131], v[88:89]
	v_pk_mul_f32 v[134:135], v[134:135], v[94:95]
	v_pk_mul_f32 v[130:131], v[160:161], v[90:91]
	v_cvt_pk_bf16_f32 v160, v132, v133
	v_cvt_pk_bf16_f32 v161, v134, v135
	v_lshl_add_u64 v[172:173], v[144:145], 1, v[172:173]
	v_cmp_lt_i32_e32 vcc, s77, v158
	v_cvt_pk_bf16_f32 v162, v128, v129
	v_cvt_pk_bf16_f32 v163, v130, v131
	global_store_dwordx4 v[172:173], v[160:163], off
	s_and_saveexec_b64 s[24:25], vcc
	s_xor_b64 s[64:65], exec, s[24:25]
	s_cbranch_execnz .LBB0_162
	s_andn2_saveexec_b64 s[64:65], s[64:65]
	s_cbranch_execnz .LBB0_163

.LBB0_133:
	s_or_b64 exec, exec, s[10:11]
	v_or_b32_e32 v158, 48, v156
	v_cmp_gt_i32_e32 vcc, s29, v158
	s_and_saveexec_b64 s[10:11], vcc
	s_cbranch_execz .LBB0_138
	v_mul_f32_e32 v129, 0xbfb8aa3b, v64
	v_mul_f32_e32 v130, 0xbfb8aa3b, v69
	v_exp_f32_e32 v129, v129
	v_exp_f32_e32 v131, v130
	v_mul_f32_e32 v130, 0xbfb8aa3b, v65
	v_exp_f32_e32 v132, v130
	v_add_f32_e32 v129, 1.0, v129
	v_rcp_f32_e32 v130, v129
	v_add_f32_e32 v129, 1.0, v131
	v_add_f32_e32 v131, 1.0, v132
	v_mul_f32_e32 v132, 0xbfb8aa3b, v70
	v_exp_f32_e32 v132, v132
	v_mul_f32_e32 v133, 0xbfb8aa3b, v66
	v_exp_f32_e32 v133, v133
	v_mul_f32_e32 v128, 0xbfb8aa3b, v68
	v_add_f32_e32 v132, 1.0, v132
	v_rcp_f32_e32 v134, v132
	v_add_f32_e32 v132, 1.0, v133
	v_mul_f32_e32 v133, 0xbfb8aa3b, v71
	v_exp_f32_e32 v133, v133
	v_mul_f32_e32 v135, 0xbfb8aa3b, v67
	v_exp_f32_e32 v128, v128
	v_exp_f32_e32 v157, v135
	v_rcp_f32_e32 v160, v132
	v_add_f32_e32 v132, 1.0, v133
	v_add_f32_e32 v128, 1.0, v128
	v_rcp_f32_e32 v135, v132
	v_add_f32_e32 v132, 1.0, v157
	v_rcp_f32_e32 v128, v128
	v_rcp_f32_e32 v129, v129
	v_rcp_f32_e32 v131, v131
	v_rcp_f32_e32 v161, v132
	v_ashrrev_i32_e32 v159, 31, v158
	v_lshlrev_b64 v[172:173], 10, v[158:159]
	v_lshl_add_u64 v[172:173], s[42:43], 0, v[172:173]
	v_pk_mul_f32 v[132:133], v[128:129], v[76:77]
	v_pk_mul_f32 v[128:129], v[130:131], v[72:73]
	v_pk_mul_f32 v[134:135], v[134:135], v[78:79]
	v_pk_mul_f32 v[130:131], v[160:161], v[74:75]
	v_cvt_pk_bf16_f32 v160, v132, v133
	v_cvt_pk_bf16_f32 v161, v134, v135
	v_lshl_add_u64 v[172:173], v[144:145], 1, v[172:173]
	v_cmp_lt_i32_e32 vcc, s77, v158
	v_cvt_pk_bf16_f32 v162, v128, v129
	v_cvt_pk_bf16_f32 v163, v130, v131
	global_store_dwordx4 v[172:173], v[160:163], off
	s_and_saveexec_b64 s[24:25], vcc
	s_xor_b64 s[64:65], exec, s[24:25]
	s_cbranch_execnz .LBB0_164
	s_andn2_saveexec_b64 s[64:65], s[64:65]
	s_cbranch_execnz .LBB0_165

.LBB0_138:
	s_or_b64 exec, exec, s[10:11]
	v_add_u32_e32 v158, 0x80, v156
	v_cmp_gt_i32_e32 vcc, s87, v156
	s_and_saveexec_b64 s[8:9], vcc
	s_cbranch_execz .LBB0_143
	v_mul_f32_e32 v129, 0xbfb8aa3b, v48
	v_mul_f32_e32 v130, 0xbfb8aa3b, v53
	v_exp_f32_e32 v129, v129
	v_exp_f32_e32 v131, v130
	v_mul_f32_e32 v130, 0xbfb8aa3b, v49
	v_exp_f32_e32 v132, v130
	v_add_f32_e32 v129, 1.0, v129
	v_rcp_f32_e32 v130, v129
	v_add_f32_e32 v129, 1.0, v131
	v_add_f32_e32 v131, 1.0, v132
	v_mul_f32_e32 v132, 0xbfb8aa3b, v54
	v_exp_f32_e32 v132, v132
	v_mul_f32_e32 v133, 0xbfb8aa3b, v50
	v_exp_f32_e32 v133, v133
	v_mul_f32_e32 v128, 0xbfb8aa3b, v52
	v_add_f32_e32 v132, 1.0, v132
	v_rcp_f32_e32 v134, v132
	v_add_f32_e32 v132, 1.0, v133
	v_mul_f32_e32 v133, 0xbfb8aa3b, v55
	v_exp_f32_e32 v133, v133
	v_mul_f32_e32 v135, 0xbfb8aa3b, v51
	v_exp_f32_e32 v128, v128
	v_exp_f32_e32 v157, v135
	v_rcp_f32_e32 v160, v132
	v_add_f32_e32 v132, 1.0, v133
	v_add_f32_e32 v128, 1.0, v128
	v_rcp_f32_e32 v135, v132
	v_add_f32_e32 v132, 1.0, v157
	v_rcp_f32_e32 v128, v128
	v_rcp_f32_e32 v129, v129
	v_rcp_f32_e32 v131, v131
	v_rcp_f32_e32 v161, v132
	v_ashrrev_i32_e32 v159, 31, v158
	v_lshlrev_b64 v[172:173], 10, v[158:159]
	v_lshl_add_u64 v[172:173], s[42:43], 0, v[172:173]
	v_pk_mul_f32 v[132:133], v[128:129], v[60:61]
	v_pk_mul_f32 v[128:129], v[130:131], v[56:57]
	v_pk_mul_f32 v[134:135], v[134:135], v[62:63]
	v_pk_mul_f32 v[130:131], v[160:161], v[58:59]
	v_cvt_pk_bf16_f32 v160, v132, v133
	v_cvt_pk_bf16_f32 v161, v134, v135
	v_lshl_add_u64 v[172:173], v[144:145], 1, v[172:173]
	v_cvt_pk_bf16_f32 v162, v128, v129
	v_cvt_pk_bf16_f32 v163, v130, v131
	global_store_dwordx4 v[172:173], v[160:163], off
	v_cmp_lt_i32_e32 vcc, s31, v156
	s_nop 0
	v_mov_b64_e32 v[160:161], 0
	s_and_saveexec_b64 s[10:11], vcc
	v_add_u32_e32 v157, 0xffffc080, v156
	v_lshrrev_b32_e32 v157, 2, v157
	v_mad_u64_u32 v[160:161], s[24:25], v157, 30, v[146:147]
	v_lshlrev_b64 v[160:161], 11, v[160:161]
	v_lshl_add_u64 v[160:161], s[52:53], 0, v[160:161]
	v_lshl_add_u64 v[160:161], v[144:145], 2, v[160:161]
	s_or_b64 exec, exec, s[10:11]
	v_cmp_ne_u64_e32 vcc, 0, v[160:161]
	s_and_b64 exec, exec, vcc
	s_cbranch_execz .LBB0_143
	global_store_dwordx4 v[160:161], v[132:135], off
	global_store_dwordx4 v[160:161], v[128:131], off offset:16
.LBB0_143:
	s_or_b64 exec, exec, s[8:9]
	v_cmp_gt_i32_e32 vcc, s26, v156
	s_and_saveexec_b64 s[8:9], vcc
	s_cbranch_execz .LBB0_148
	v_mul_f32_e32 v129, 0xbfb8aa3b, v32
	v_mul_f32_e32 v130, 0xbfb8aa3b, v37
	v_exp_f32_e32 v129, v129
	v_exp_f32_e32 v131, v130
	v_mul_f32_e32 v130, 0xbfb8aa3b, v33
	v_exp_f32_e32 v132, v130
	v_add_f32_e32 v129, 1.0, v129
	v_rcp_f32_e32 v130, v129
	v_add_f32_e32 v129, 1.0, v131
	v_add_f32_e32 v131, 1.0, v132
	v_mul_f32_e32 v132, 0xbfb8aa3b, v38
	v_exp_f32_e32 v132, v132
	v_mul_f32_e32 v133, 0xbfb8aa3b, v34
	v_exp_f32_e32 v133, v133
	v_mul_f32_e32 v128, 0xbfb8aa3b, v36
	v_add_f32_e32 v132, 1.0, v132
	v_rcp_f32_e32 v134, v132
	v_add_f32_e32 v132, 1.0, v133
	v_mul_f32_e32 v133, 0xbfb8aa3b, v39
	v_exp_f32_e32 v133, v133
	v_mul_f32_e32 v135, 0xbfb8aa3b, v35
	v_exp_f32_e32 v128, v128
	v_exp_f32_e32 v157, v135
	v_rcp_f32_e32 v160, v132
	v_add_f32_e32 v132, 1.0, v133
	v_add_f32_e32 v128, 1.0, v128
	v_rcp_f32_e32 v135, v132
	v_add_f32_e32 v132, 1.0, v157
	v_ashrrev_i32_e32 v157, 31, v156
	v_rcp_f32_e32 v128, v128
	v_rcp_f32_e32 v129, v129
	v_rcp_f32_e32 v131, v131
	v_rcp_f32_e32 v161, v132
	v_lshlrev_b64 v[172:173], 10, v[156:157]
	v_lshl_add_u64 v[172:173], s[42:43], 0, v[172:173]
	v_lshl_add_u64 v[172:173], v[144:145], 1, v[172:173]
	v_add_co_u32_e32 v172, vcc, 0x24000, v172
	v_pk_mul_f32 v[132:133], v[128:129], v[44:45]
	v_pk_mul_f32 v[128:129], v[130:131], v[40:41]
	v_pk_mul_f32 v[134:135], v[134:135], v[46:47]
	v_pk_mul_f32 v[130:131], v[160:161], v[42:43]
	v_cvt_pk_bf16_f32 v160, v132, v133
	v_cvt_pk_bf16_f32 v161, v134, v135
	v_addc_co_u32_e32 v173, vcc, 0, v173, vcc
	v_cvt_pk_bf16_f32 v162, v128, v129
	v_cvt_pk_bf16_f32 v163, v130, v131
	global_store_dwordx4 v[172:173], v[160:163], off
	v_cmp_lt_i32_e32 vcc, s27, v156
	s_nop 0
	v_mov_b64_e32 v[160:161], 0
	s_and_saveexec_b64 s[10:11], vcc
	v_add_u32_e32 v157, 0xffffc090, v156
	v_lshrrev_b32_e32 v157, 2, v157
	v_mad_u64_u32 v[160:161], s[24:25], v157, 30, v[146:147]
	v_lshlrev_b64 v[160:161], 11, v[160:161]
	v_lshl_add_u64 v[160:161], s[52:53], 0, v[160:161]
	v_lshl_add_u64 v[160:161], v[144:145], 2, v[160:161]
	s_or_b64 exec, exec, s[10:11]
	v_cmp_ne_u64_e32 vcc, 0, v[160:161]
	s_and_b64 exec, exec, vcc
	s_cbranch_execz .LBB0_148
	global_store_dwordx4 v[160:161], v[132:135], off
	global_store_dwordx4 v[160:161], v[128:131], off offset:16
.LBB0_148:
	s_or_b64 exec, exec, s[8:9]
	s_nop 0
	v_ashrrev_i32_e32 v128, 11, v158
	v_mul_i32_i24_e32 v158, 30, v128
	v_ashrrev_i32_e32 v159, 31, v158
	v_cmp_gt_i32_e32 vcc, s14, v156
	s_and_saveexec_b64 s[8:9], vcc
	s_cbranch_execz .LBB0_153
	v_mul_f32_e32 v129, 0xbfb8aa3b, v16
	v_mul_f32_e32 v130, 0xbfb8aa3b, v21
	v_exp_f32_e32 v129, v129
	v_exp_f32_e32 v131, v130
	v_mul_f32_e32 v130, 0xbfb8aa3b, v17
	v_exp_f32_e32 v132, v130
	v_add_f32_e32 v129, 1.0, v129
	v_rcp_f32_e32 v130, v129
	v_add_f32_e32 v129, 1.0, v131
	v_add_f32_e32 v131, 1.0, v132
	v_mul_f32_e32 v132, 0xbfb8aa3b, v22
	v_exp_f32_e32 v132, v132
	v_mul_f32_e32 v133, 0xbfb8aa3b, v18
	v_exp_f32_e32 v133, v133
	v_mul_f32_e32 v128, 0xbfb8aa3b, v20
	v_add_f32_e32 v132, 1.0, v132
	v_rcp_f32_e32 v134, v132
	v_add_f32_e32 v132, 1.0, v133
	v_mul_f32_e32 v133, 0xbfb8aa3b, v23
	v_exp_f32_e32 v133, v133
	v_mul_f32_e32 v135, 0xbfb8aa3b, v19
	v_exp_f32_e32 v128, v128
	v_exp_f32_e32 v157, v135
	v_rcp_f32_e32 v162, v132
	v_add_f32_e32 v132, 1.0, v133
	v_add_f32_e32 v128, 1.0, v128
	v_rcp_f32_e32 v135, v132
	v_add_f32_e32 v132, 1.0, v157
	v_rcp_f32_e32 v128, v128
	v_rcp_f32_e32 v129, v129
	v_rcp_f32_e32 v131, v131
	v_rcp_f32_e32 v163, v132
	v_add_u32_e32 v160, 0xa0, v156
	v_ashrrev_i32_e32 v161, 31, v160
	v_pk_mul_f32 v[132:133], v[128:129], v[28:29]
	v_pk_mul_f32 v[128:129], v[130:131], v[24:25]
	v_pk_mul_f32 v[130:131], v[162:163], v[26:27]
	v_lshlrev_b64 v[162:163], 10, v[160:161]
	v_lshl_add_u64 v[162:163], s[42:43], 0, v[162:163]
	v_pk_mul_f32 v[134:135], v[134:135], v[30:31]
	v_lshl_add_u64 v[162:163], v[144:145], 1, v[162:163]
	v_cmp_lt_i32_e32 vcc, s15, v156
	v_cvt_pk_bf16_f32 v172, v132, v133
	v_cvt_pk_bf16_f32 v173, v134, v135
	v_cvt_pk_bf16_f32 v174, v128, v129
	v_cvt_pk_bf16_f32 v175, v130, v131
	global_store_dwordx4 v[162:163], v[172:175], off
	s_and_saveexec_b64 s[10:11], vcc
	s_xor_b64 s[10:11], exec, s[10:11]
	s_cbranch_execnz .LBB0_166
	s_andn2_saveexec_b64 s[10:11], s[10:11]
	s_cbranch_execnz .LBB0_167

.LBB0_153:
	s_or_b64 exec, exec, s[8:9]
	v_cmp_gt_i32_e32 vcc, s81, v156
	s_and_saveexec_b64 s[8:9], vcc
	s_cbranch_execz .LBB0_158
	v_mul_f32_e32 v129, 0xbfb8aa3b, v0
	v_mul_f32_e32 v130, 0xbfb8aa3b, v5
	v_exp_f32_e32 v129, v129
	v_exp_f32_e32 v131, v130
	v_mul_f32_e32 v130, 0xbfb8aa3b, v1
	v_exp_f32_e32 v132, v130
	v_add_f32_e32 v129, 1.0, v129
	v_rcp_f32_e32 v130, v129
	v_add_f32_e32 v129, 1.0, v131
	v_add_f32_e32 v131, 1.0, v132
	v_mul_f32_e32 v132, 0xbfb8aa3b, v6
	v_exp_f32_e32 v132, v132
	v_mul_f32_e32 v133, 0xbfb8aa3b, v2
	v_exp_f32_e32 v133, v133
	v_mul_f32_e32 v128, 0xbfb8aa3b, v4
	v_add_f32_e32 v132, 1.0, v132
	v_rcp_f32_e32 v134, v132
	v_add_f32_e32 v132, 1.0, v133
	v_mul_f32_e32 v133, 0xbfb8aa3b, v7
	v_exp_f32_e32 v133, v133
	v_mul_f32_e32 v135, 0xbfb8aa3b, v3
	v_exp_f32_e32 v128, v128
	v_exp_f32_e32 v157, v135
	v_rcp_f32_e32 v162, v132
	v_add_f32_e32 v132, 1.0, v133
	v_add_f32_e32 v128, 1.0, v128
	v_rcp_f32_e32 v135, v132
	v_add_f32_e32 v132, 1.0, v157
	v_rcp_f32_e32 v128, v128
	v_rcp_f32_e32 v129, v129
	v_rcp_f32_e32 v131, v131
	v_rcp_f32_e32 v163, v132
	v_add_u32_e32 v160, 0xb0, v156
	v_ashrrev_i32_e32 v161, 31, v160
	v_pk_mul_f32 v[132:133], v[128:129], v[12:13]
	v_pk_mul_f32 v[128:129], v[130:131], v[8:9]
	v_pk_mul_f32 v[130:131], v[162:163], v[10:11]
	v_lshlrev_b64 v[162:163], 10, v[160:161]
	v_lshl_add_u64 v[162:163], s[42:43], 0, v[162:163]
	v_pk_mul_f32 v[134:135], v[134:135], v[14:15]
	v_lshl_add_u64 v[162:163], v[144:145], 1, v[162:163]
	v_cmp_lt_i32_e32 vcc, s80, v156
	v_cvt_pk_bf16_f32 v172, v132, v133
	v_cvt_pk_bf16_f32 v173, v134, v135
	v_cvt_pk_bf16_f32 v174, v128, v129
	v_cvt_pk_bf16_f32 v175, v130, v131
	global_store_dwordx4 v[162:163], v[172:175], off
	s_and_saveexec_b64 s[10:11], vcc
	s_xor_b64 s[10:11], exec, s[10:11]
	s_cbranch_execnz .LBB0_168
	s_andn2_saveexec_b64 s[10:11], s[10:11]
	s_cbranch_execnz .LBB0_169

.LBB0_159:
	s_lshl_b32 s8, s66, 8
	s_and_b32 s8, s8, 0x100
	s_cmp_gt_u32 s66, 1
	v_or_b32_e32 v158, s8, v166
	s_cselect_b64 s[10:11], -1, 0
	s_and_b32 s8, s66, -2
	s_cmp_eq_u32 s8, 2
	s_cselect_b64 s[64:65], -1, 0
	s_and_b64 s[8:9], s[64:65], exec
	s_mov_b32 s8, 0x203e000
	s_cselect_b32 s72, s8, 0x204e000
	s_mov_b32 s8, 0x1020000
	s_cselect_b32 s24, s8, 0x1820000
	s_and_saveexec_b64 s[66:67], s[6:7]
	s_cbranch_execz .LBB0_184
	v_ashrrev_i32_e32 v157, 31, v156
	v_add_u32_e32 v144, 0xffffc000, v156
	v_lshlrev_b64 v[130:131], 9, v[156:157]
	v_cmp_gt_i32_e64 s[8:9], s87, v156
	v_lshlrev_b64 v[128:129], 11, v[144:145]
	v_cmp_lt_i32_e64 s[6:7], s77, v156
	s_and_b64 vcc, exec, s[10:11]
	s_cbranch_vccz .LBB0_170
	s_and_b64 s[68:69], s[64:65], exec
	s_cselect_b32 s25, s89, s91
	s_cselect_b32 s68, s88, s90
	v_mov_b32_e32 v160, s68
	v_mov_b32_e32 v161, s25
	s_lshl_b32 s25, s24, 2
	v_lshl_add_u64 v[160:161], v[130:131], 1, v[160:161]
	v_lshlrev_b32_e32 v144, 1, v158
	s_add_u32 s68, s16, s25
	v_cvt_pk_bf16_f32 v132, v124, v125
	v_cvt_pk_bf16_f32 v133, v126, v127
	v_lshl_add_u64 v[160:161], v[160:161], 0, v[144:145]
	s_addc_u32 s69, s17, 0
	s_lshl_b32 s25, s72, 2
	v_cvt_pk_bf16_f32 v134, v120, v121
	v_cvt_pk_bf16_f32 v135, v122, v123
	global_store_dwordx4 v[160:161], v[132:135], off
	v_lshlrev_b32_e32 v144, 2, v158
	s_nop 0
	v_lshl_add_u64 v[132:133], v[130:131], 2, s[68:69]
	s_add_u32 s68, s16, s25
	s_addc_u32 s69, s17, 0
	v_lshl_add_u64 v[134:135], s[68:69], 0, v[128:129]
	v_cndmask_b32_e64 v133, v135, v133, s[8:9]
	v_cndmask_b32_e64 v132, v134, v132, s[8:9]
	v_lshl_add_u64 v[134:135], v[132:133], 0, v[144:145]
	global_store_dwordx4 v[134:135], v[124:127], off
	s_mov_b64 s[68:69], -1
	v_lshlrev_b64 v[132:133], 10, v[156:157]
	v_lshl_add_u64 v[132:133], s[40:41], 0, v[132:133]
	s_cbranch_execz .LBB0_171
	s_branch .LBB0_174

.LBB0_171:
	v_lshlrev_b32_e32 v144, 1, v158
	v_pk_mul_f32 v[126:127], v[126:127], s[56:57] op_sel_hi:[1,0]
	v_pk_mul_f32 v[124:125], v[124:125], s[56:57] op_sel_hi:[1,0]
	v_pk_mul_f32 v[122:123], v[122:123], s[56:57] op_sel_hi:[1,0]
	v_pk_mul_f32 v[120:121], v[120:121], s[56:57] op_sel_hi:[1,0]
	v_lshl_add_u64 v[134:135], v[132:133], 0, v[144:145]
	v_cvt_pk_bf16_f32 v160, v124, v125
	v_cvt_pk_bf16_f32 v161, v126, v127
	v_cvt_pk_bf16_f32 v162, v120, v121
	v_cvt_pk_bf16_f32 v163, v122, v123
	global_store_dwordx4 v[134:135], v[160:163], off
	s_and_saveexec_b64 s[70:71], s[6:7]
	s_cbranch_execz .LBB0_173
	v_lshl_add_u64 v[134:135], s[44:45], 0, v[128:129]
	v_lshlrev_b32_e32 v144, 2, v158
	v_lshl_add_u64 v[134:135], v[134:135], 0, v[144:145]
	s_or_b64 s[68:69], s[68:69], exec
	global_store_dwordx4 v[134:135], v[124:127], off

.LBB0_176:
	s_and_b64 s[68:69], s[64:65], exec
	s_cselect_b32 s25, s89, s91
	s_cselect_b32 s68, s88, s90
	v_mov_b32_e32 v124, s68
	v_mov_b32_e32 v125, s25
	s_lshl_b32 s25, s24, 2
	v_lshl_add_u64 v[124:125], v[130:131], 1, v[124:125]
	v_lshlrev_b32_e32 v144, 1, v158
	s_add_u32 s68, s16, s25
	v_cvt_pk_bf16_f32 v120, v116, v117
	v_cvt_pk_bf16_f32 v121, v118, v119
	v_lshl_add_u64 v[124:125], v[124:125], 0, v[144:145]
	s_addc_u32 s69, s17, 0
	s_lshl_b32 s25, s72, 2
	v_cvt_pk_bf16_f32 v122, v112, v113
	v_cvt_pk_bf16_f32 v123, v114, v115
	global_store_dwordx4 v[124:125], v[120:123], off offset:256
	v_lshlrev_b32_e32 v144, 2, v158
	s_nop 0
	v_lshl_add_u64 v[120:121], v[130:131], 2, s[68:69]
	s_add_u32 s68, s16, s25
	s_addc_u32 s69, s17, 0
	v_lshl_add_u64 v[122:123], s[68:69], 0, v[128:129]
	v_cndmask_b32_e64 v121, v123, v121, s[8:9]
	v_cndmask_b32_e64 v120, v122, v120, s[8:9]
	v_lshl_add_u64 v[122:123], v[120:121], 0, v[144:145]
	v_lshl_add_u64 v[120:121], v[122:123], 0, s[58:59]
	s_mov_b64 s[8:9], -1
	global_store_dwordx4 v[122:123], v[116:119], off offset:512
	s_cbranch_execz .LBB0_179
	s_branch .LBB0_182

.LBB0_179:
	v_lshlrev_b32_e32 v144, 1, v158
	v_pk_mul_f32 v[118:119], v[118:119], s[56:57] op_sel_hi:[1,0]
	v_pk_mul_f32 v[116:117], v[116:117], s[56:57] op_sel_hi:[1,0]
	v_pk_mul_f32 v[114:115], v[114:115], s[56:57] op_sel_hi:[1,0]
	v_pk_mul_f32 v[112:113], v[112:113], s[56:57] op_sel_hi:[1,0]
	v_cvt_pk_bf16_f32 v120, v116, v117
	v_cvt_pk_bf16_f32 v121, v118, v119
	v_lshl_add_u64 v[124:125], v[132:133], 0, v[144:145]
	v_cvt_pk_bf16_f32 v122, v112, v113
	v_cvt_pk_bf16_f32 v123, v114, v115
	global_store_dwordx4 v[124:125], v[120:123], off offset:256
	s_and_saveexec_b64 s[68:69], s[6:7]
	s_cbranch_execz .LBB0_181
	v_lshl_add_u64 v[120:121], s[44:45], 0, v[128:129]
	v_lshlrev_b32_e32 v144, 2, v158
	v_lshl_add_u64 v[122:123], v[120:121], 0, v[144:145]
	v_lshl_add_u64 v[120:121], v[122:123], 0, s[58:59]
	s_or_b64 s[8:9], s[8:9], exec
	global_store_dwordx4 v[122:123], v[116:119], off offset:512

.LBB0_184:
	s_or_b64 exec, exec, s[66:67]
	v_or_b32_e32 v116, 16, v156
	v_cndmask_b32_e64 v112, 0, 1, s[10:11]
	v_cmp_gt_i32_e32 vcc, s29, v116
	v_cmp_ne_u32_e64 s[6:7], 1, v112
	s_and_saveexec_b64 s[66:67], vcc
	s_cbranch_execz .LBB0_201
	v_ashrrev_i32_e32 v117, 31, v116
	v_add_u32_e32 v144, 0xffffc010, v156
	v_lshlrev_b64 v[114:115], 9, v[116:117]
	v_cmp_gt_i32_e64 s[10:11], s87, v116
	v_lshlrev_b64 v[112:113], 11, v[144:145]
	s_and_b64 vcc, exec, s[6:7]
	v_cmp_lt_i32_e64 s[8:9], s77, v116
	s_cbranch_vccnz .LBB0_187
	s_and_b64 s[68:69], s[64:65], exec
	s_cselect_b32 s25, s89, s91
	s_cselect_b32 s68, s88, s90
	v_mov_b32_e32 v122, s68
	v_mov_b32_e32 v123, s25
	s_lshl_b32 s25, s24, 2
	v_lshl_add_u64 v[122:123], v[114:115], 1, v[122:123]
	v_lshlrev_b32_e32 v144, 1, v158
	s_add_u32 s68, s16, s25
	v_cvt_pk_bf16_f32 v118, v108, v109
	v_cvt_pk_bf16_f32 v119, v110, v111
	v_lshl_add_u64 v[122:123], v[122:123], 0, v[144:145]
	s_addc_u32 s69, s17, 0
	s_lshl_b32 s25, s72, 2
	v_cvt_pk_bf16_f32 v120, v104, v105
	v_cvt_pk_bf16_f32 v121, v106, v107
	global_store_dwordx4 v[122:123], v[118:121], off
	v_lshlrev_b32_e32 v144, 2, v158
	s_nop 0
	v_lshl_add_u64 v[118:119], v[114:115], 2, s[68:69]
	s_add_u32 s68, s16, s25
	s_addc_u32 s69, s17, 0
	v_lshl_add_u64 v[120:121], s[68:69], 0, v[112:113]
	v_cndmask_b32_e64 v119, v121, v119, s[10:11]
	v_cndmask_b32_e64 v118, v120, v118, s[10:11]
	v_lshl_add_u64 v[118:119], v[118:119], 0, v[144:145]
	s_mov_b64 s[68:69], -1
	global_store_dwordx4 v[118:119], v[108:111], off
	v_lshlrev_b64 v[116:117], 10, v[116:117]
	v_lshl_add_u64 v[116:117], s[40:41], 0, v[116:117]
	s_cbranch_execz .LBB0_188
	s_branch .LBB0_191

.LBB0_188:
	v_lshlrev_b32_e32 v144, 1, v158
	v_pk_mul_f32 v[110:111], v[110:111], s[56:57] op_sel_hi:[1,0]
	v_pk_mul_f32 v[108:109], v[108:109], s[56:57] op_sel_hi:[1,0]
	v_pk_mul_f32 v[106:107], v[106:107], s[56:57] op_sel_hi:[1,0]
	v_pk_mul_f32 v[104:105], v[104:105], s[56:57] op_sel_hi:[1,0]
	v_cvt_pk_bf16_f32 v118, v108, v109
	v_cvt_pk_bf16_f32 v119, v110, v111
	v_lshl_add_u64 v[122:123], v[116:117], 0, v[144:145]
	v_cvt_pk_bf16_f32 v120, v104, v105
	v_cvt_pk_bf16_f32 v121, v106, v107
	global_store_dwordx4 v[122:123], v[118:121], off
	s_and_saveexec_b64 s[70:71], s[8:9]
	s_cbranch_execz .LBB0_190
	v_lshl_add_u64 v[118:119], s[44:45], 0, v[112:113]
	v_lshlrev_b32_e32 v144, 2, v158
	v_lshl_add_u64 v[118:119], v[118:119], 0, v[144:145]
	s_or_b64 s[68:69], s[68:69], exec
	global_store_dwordx4 v[118:119], v[108:111], off

.LBB0_193:
	s_and_b64 s[68:69], s[64:65], exec
	s_cselect_b32 s25, s89, s91
	s_cselect_b32 s68, s88, s90
	v_mov_b32_e32 v108, s68
	v_mov_b32_e32 v109, s25
	s_lshl_b32 s25, s24, 2
	v_lshl_add_u64 v[108:109], v[114:115], 1, v[108:109]
	v_lshlrev_b32_e32 v144, 1, v158
	s_add_u32 s68, s16, s25
	v_cvt_pk_bf16_f32 v104, v100, v101
	v_cvt_pk_bf16_f32 v105, v102, v103
	v_lshl_add_u64 v[108:109], v[108:109], 0, v[144:145]
	s_addc_u32 s69, s17, 0
	s_lshl_b32 s25, s72, 2
	v_cvt_pk_bf16_f32 v106, v96, v97
	v_cvt_pk_bf16_f32 v107, v98, v99
	global_store_dwordx4 v[108:109], v[104:107], off offset:256
	v_lshlrev_b32_e32 v144, 2, v158
	s_nop 0
	v_lshl_add_u64 v[104:105], v[114:115], 2, s[68:69]
	s_add_u32 s68, s16, s25
	s_addc_u32 s69, s17, 0
	v_lshl_add_u64 v[106:107], s[68:69], 0, v[112:113]
	v_cndmask_b32_e64 v105, v107, v105, s[10:11]
	v_cndmask_b32_e64 v104, v106, v104, s[10:11]
	v_lshl_add_u64 v[106:107], v[104:105], 0, v[144:145]
	v_lshl_add_u64 v[104:105], v[106:107], 0, s[58:59]
	s_mov_b64 s[10:11], -1
	global_store_dwordx4 v[106:107], v[100:103], off offset:512
	s_cbranch_execz .LBB0_196
	s_branch .LBB0_199

.LBB0_196:
	v_lshlrev_b32_e32 v144, 1, v158
	v_pk_mul_f32 v[102:103], v[102:103], s[56:57] op_sel_hi:[1,0]
	v_pk_mul_f32 v[100:101], v[100:101], s[56:57] op_sel_hi:[1,0]
	v_pk_mul_f32 v[98:99], v[98:99], s[56:57] op_sel_hi:[1,0]
	v_pk_mul_f32 v[96:97], v[96:97], s[56:57] op_sel_hi:[1,0]
	v_cvt_pk_bf16_f32 v104, v100, v101
	v_cvt_pk_bf16_f32 v105, v102, v103
	v_lshl_add_u64 v[108:109], v[116:117], 0, v[144:145]
	v_cvt_pk_bf16_f32 v106, v96, v97
	v_cvt_pk_bf16_f32 v107, v98, v99
	global_store_dwordx4 v[108:109], v[104:107], off offset:256
	s_and_saveexec_b64 s[68:69], s[8:9]
	s_cbranch_execz .LBB0_198
	v_lshl_add_u64 v[104:105], s[44:45], 0, v[112:113]
	v_lshlrev_b32_e32 v144, 2, v158
	v_lshl_add_u64 v[106:107], v[104:105], 0, v[144:145]
	v_lshl_add_u64 v[104:105], v[106:107], 0, s[58:59]
	s_or_b64 s[10:11], s[10:11], exec
	global_store_dwordx4 v[106:107], v[100:103], off offset:512

.LBB0_201:
	s_or_b64 exec, exec, s[66:67]
	v_or_b32_e32 v100, 32, v156
	v_cmp_gt_i32_e32 vcc, s29, v100
	s_and_saveexec_b64 s[66:67], vcc
	s_cbranch_execz .LBB0_218
	v_ashrrev_i32_e32 v101, 31, v100
	v_add_u32_e32 v144, 0xffffc020, v156
	v_lshlrev_b64 v[98:99], 9, v[100:101]
	v_cmp_gt_i32_e64 s[10:11], s87, v100
	v_lshlrev_b64 v[96:97], 11, v[144:145]
	s_and_b64 vcc, exec, s[6:7]
	v_cmp_lt_i32_e64 s[8:9], s77, v100
	s_cbranch_vccnz .LBB0_204
	s_and_b64 s[68:69], s[64:65], exec
	s_cselect_b32 s25, s89, s91
	s_cselect_b32 s68, s88, s90
	v_mov_b32_e32 v106, s68
	v_mov_b32_e32 v107, s25
	s_lshl_b32 s25, s24, 2
	v_lshl_add_u64 v[106:107], v[98:99], 1, v[106:107]
	v_lshlrev_b32_e32 v144, 1, v158
	s_add_u32 s68, s16, s25
	v_cvt_pk_bf16_f32 v102, v92, v93
	v_cvt_pk_bf16_f32 v103, v94, v95
	v_lshl_add_u64 v[106:107], v[106:107], 0, v[144:145]
	s_addc_u32 s69, s17, 0
	s_lshl_b32 s25, s72, 2
	v_cvt_pk_bf16_f32 v104, v88, v89
	v_cvt_pk_bf16_f32 v105, v90, v91
	global_store_dwordx4 v[106:107], v[102:105], off
	v_lshlrev_b32_e32 v144, 2, v158
	s_nop 0
	v_lshl_add_u64 v[102:103], v[98:99], 2, s[68:69]
	s_add_u32 s68, s16, s25
	s_addc_u32 s69, s17, 0
	v_lshl_add_u64 v[104:105], s[68:69], 0, v[96:97]
	v_cndmask_b32_e64 v103, v105, v103, s[10:11]
	v_cndmask_b32_e64 v102, v104, v102, s[10:11]
	v_lshl_add_u64 v[102:103], v[102:103], 0, v[144:145]
	s_mov_b64 s[68:69], -1
	global_store_dwordx4 v[102:103], v[92:95], off
	v_lshlrev_b64 v[100:101], 10, v[100:101]
	v_lshl_add_u64 v[100:101], s[40:41], 0, v[100:101]
	s_cbranch_execz .LBB0_205
	s_branch .LBB0_208

.LBB0_205:
	v_lshlrev_b32_e32 v144, 1, v158
	v_pk_mul_f32 v[94:95], v[94:95], s[56:57] op_sel_hi:[1,0]
	v_pk_mul_f32 v[92:93], v[92:93], s[56:57] op_sel_hi:[1,0]
	v_pk_mul_f32 v[90:91], v[90:91], s[56:57] op_sel_hi:[1,0]
	v_pk_mul_f32 v[88:89], v[88:89], s[56:57] op_sel_hi:[1,0]
	v_cvt_pk_bf16_f32 v102, v92, v93
	v_cvt_pk_bf16_f32 v103, v94, v95
	v_lshl_add_u64 v[106:107], v[100:101], 0, v[144:145]
	v_cvt_pk_bf16_f32 v104, v88, v89
	v_cvt_pk_bf16_f32 v105, v90, v91
	global_store_dwordx4 v[106:107], v[102:105], off
	s_and_saveexec_b64 s[70:71], s[8:9]
	s_cbranch_execz .LBB0_207
	v_lshl_add_u64 v[102:103], s[44:45], 0, v[96:97]
	v_lshlrev_b32_e32 v144, 2, v158
	v_lshl_add_u64 v[102:103], v[102:103], 0, v[144:145]
	s_or_b64 s[68:69], s[68:69], exec
	global_store_dwordx4 v[102:103], v[92:95], off

.LBB0_210:
	s_and_b64 s[68:69], s[64:65], exec
	s_cselect_b32 s25, s89, s91
	s_cselect_b32 s68, s88, s90
	v_mov_b32_e32 v92, s68
	v_mov_b32_e32 v93, s25
	s_lshl_b32 s25, s24, 2
	v_lshl_add_u64 v[92:93], v[98:99], 1, v[92:93]
	v_lshlrev_b32_e32 v144, 1, v158
	s_add_u32 s68, s16, s25
	v_cvt_pk_bf16_f32 v88, v84, v85
	v_cvt_pk_bf16_f32 v89, v86, v87
	v_lshl_add_u64 v[92:93], v[92:93], 0, v[144:145]
	s_addc_u32 s69, s17, 0
	s_lshl_b32 s25, s72, 2
	v_cvt_pk_bf16_f32 v90, v80, v81
	v_cvt_pk_bf16_f32 v91, v82, v83
	global_store_dwordx4 v[92:93], v[88:91], off offset:256
	v_lshlrev_b32_e32 v144, 2, v158
	s_nop 0
	v_lshl_add_u64 v[88:89], v[98:99], 2, s[68:69]
	s_add_u32 s68, s16, s25
	s_addc_u32 s69, s17, 0
	v_lshl_add_u64 v[90:91], s[68:69], 0, v[96:97]
	v_cndmask_b32_e64 v89, v91, v89, s[10:11]
	v_cndmask_b32_e64 v88, v90, v88, s[10:11]
	v_lshl_add_u64 v[90:91], v[88:89], 0, v[144:145]
	v_lshl_add_u64 v[88:89], v[90:91], 0, s[58:59]
	s_mov_b64 s[10:11], -1
	global_store_dwordx4 v[90:91], v[84:87], off offset:512
	s_cbranch_execz .LBB0_213
	s_branch .LBB0_216

.LBB0_213:
	v_lshlrev_b32_e32 v144, 1, v158
	v_pk_mul_f32 v[86:87], v[86:87], s[56:57] op_sel_hi:[1,0]
	v_pk_mul_f32 v[84:85], v[84:85], s[56:57] op_sel_hi:[1,0]
	v_pk_mul_f32 v[82:83], v[82:83], s[56:57] op_sel_hi:[1,0]
	v_pk_mul_f32 v[80:81], v[80:81], s[56:57] op_sel_hi:[1,0]
	v_cvt_pk_bf16_f32 v88, v84, v85
	v_cvt_pk_bf16_f32 v89, v86, v87
	v_lshl_add_u64 v[92:93], v[100:101], 0, v[144:145]
	v_cvt_pk_bf16_f32 v90, v80, v81
	v_cvt_pk_bf16_f32 v91, v82, v83
	global_store_dwordx4 v[92:93], v[88:91], off offset:256
	s_and_saveexec_b64 s[68:69], s[8:9]
	s_cbranch_execz .LBB0_215
	v_lshl_add_u64 v[88:89], s[44:45], 0, v[96:97]
	v_lshlrev_b32_e32 v144, 2, v158
	v_lshl_add_u64 v[90:91], v[88:89], 0, v[144:145]
	v_lshl_add_u64 v[88:89], v[90:91], 0, s[58:59]
	s_or_b64 s[10:11], s[10:11], exec
	global_store_dwordx4 v[90:91], v[84:87], off offset:512

.LBB0_218:
	s_or_b64 exec, exec, s[66:67]
	v_or_b32_e32 v84, 48, v156
	v_cmp_gt_i32_e32 vcc, s29, v84
	s_and_saveexec_b64 s[66:67], vcc
	s_cbranch_execz .LBB0_235
	v_ashrrev_i32_e32 v85, 31, v84
	v_add_u32_e32 v144, 0xffffc030, v156
	v_lshlrev_b64 v[82:83], 9, v[84:85]
	v_cmp_gt_i32_e64 s[10:11], s87, v84
	v_lshlrev_b64 v[80:81], 11, v[144:145]
	s_and_b64 vcc, exec, s[6:7]
	v_cmp_lt_i32_e64 s[8:9], s77, v84
	s_cbranch_vccnz .LBB0_221
	s_and_b64 s[68:69], s[64:65], exec
	s_cselect_b32 s25, s89, s91
	s_cselect_b32 s68, s88, s90
	v_mov_b32_e32 v90, s68
	v_mov_b32_e32 v91, s25
	s_lshl_b32 s25, s24, 2
	v_lshl_add_u64 v[90:91], v[82:83], 1, v[90:91]
	v_lshlrev_b32_e32 v144, 1, v158
	s_add_u32 s68, s16, s25
	v_cvt_pk_bf16_f32 v86, v76, v77
	v_cvt_pk_bf16_f32 v87, v78, v79
	v_lshl_add_u64 v[90:91], v[90:91], 0, v[144:145]
	s_addc_u32 s69, s17, 0
	s_lshl_b32 s25, s72, 2
	v_cvt_pk_bf16_f32 v88, v72, v73
	v_cvt_pk_bf16_f32 v89, v74, v75
	global_store_dwordx4 v[90:91], v[86:89], off
	v_lshlrev_b32_e32 v144, 2, v158
	s_nop 0
	v_lshl_add_u64 v[86:87], v[82:83], 2, s[68:69]
	s_add_u32 s68, s16, s25
	s_addc_u32 s69, s17, 0
	v_lshl_add_u64 v[88:89], s[68:69], 0, v[80:81]
	v_cndmask_b32_e64 v87, v89, v87, s[10:11]
	v_cndmask_b32_e64 v86, v88, v86, s[10:11]
	v_lshl_add_u64 v[86:87], v[86:87], 0, v[144:145]
	s_mov_b64 s[68:69], -1
	global_store_dwordx4 v[86:87], v[76:79], off
	v_lshlrev_b64 v[84:85], 10, v[84:85]
	v_lshl_add_u64 v[84:85], s[40:41], 0, v[84:85]
	s_cbranch_execz .LBB0_222
	s_branch .LBB0_225

.LBB0_222:
	v_lshlrev_b32_e32 v144, 1, v158
	v_pk_mul_f32 v[78:79], v[78:79], s[56:57] op_sel_hi:[1,0]
	v_pk_mul_f32 v[76:77], v[76:77], s[56:57] op_sel_hi:[1,0]
	v_pk_mul_f32 v[74:75], v[74:75], s[56:57] op_sel_hi:[1,0]
	v_pk_mul_f32 v[72:73], v[72:73], s[56:57] op_sel_hi:[1,0]
	v_cvt_pk_bf16_f32 v86, v76, v77
	v_cvt_pk_bf16_f32 v87, v78, v79
	v_lshl_add_u64 v[90:91], v[84:85], 0, v[144:145]
	v_cvt_pk_bf16_f32 v88, v72, v73
	v_cvt_pk_bf16_f32 v89, v74, v75
	global_store_dwordx4 v[90:91], v[86:89], off
	s_and_saveexec_b64 s[70:71], s[8:9]
	s_cbranch_execz .LBB0_224
	v_lshl_add_u64 v[86:87], s[44:45], 0, v[80:81]
	v_lshlrev_b32_e32 v144, 2, v158
	v_lshl_add_u64 v[86:87], v[86:87], 0, v[144:145]
	s_or_b64 s[68:69], s[68:69], exec
	global_store_dwordx4 v[86:87], v[76:79], off

.LBB0_227:
	s_and_b64 s[68:69], s[64:65], exec
	s_cselect_b32 s25, s89, s91
	s_cselect_b32 s68, s88, s90
	v_mov_b32_e32 v76, s68
	v_mov_b32_e32 v77, s25
	s_lshl_b32 s25, s24, 2
	v_lshl_add_u64 v[76:77], v[82:83], 1, v[76:77]
	v_lshlrev_b32_e32 v144, 1, v158
	s_add_u32 s68, s16, s25
	v_cvt_pk_bf16_f32 v72, v68, v69
	v_cvt_pk_bf16_f32 v73, v70, v71
	v_lshl_add_u64 v[76:77], v[76:77], 0, v[144:145]
	s_addc_u32 s69, s17, 0
	s_lshl_b32 s25, s72, 2
	v_cvt_pk_bf16_f32 v74, v64, v65
	v_cvt_pk_bf16_f32 v75, v66, v67
	global_store_dwordx4 v[76:77], v[72:75], off offset:256
	v_lshlrev_b32_e32 v144, 2, v158
	s_nop 0
	v_lshl_add_u64 v[72:73], v[82:83], 2, s[68:69]
	s_add_u32 s68, s16, s25
	s_addc_u32 s69, s17, 0
	v_lshl_add_u64 v[74:75], s[68:69], 0, v[80:81]
	v_cndmask_b32_e64 v73, v75, v73, s[10:11]
	v_cndmask_b32_e64 v72, v74, v72, s[10:11]
	v_lshl_add_u64 v[74:75], v[72:73], 0, v[144:145]
	v_lshl_add_u64 v[72:73], v[74:75], 0, s[58:59]
	s_mov_b64 s[10:11], -1
	global_store_dwordx4 v[74:75], v[68:71], off offset:512
	s_cbranch_execz .LBB0_230
	s_branch .LBB0_233

.LBB0_230:
	v_lshlrev_b32_e32 v144, 1, v158
	v_pk_mul_f32 v[70:71], v[70:71], s[56:57] op_sel_hi:[1,0]
	v_pk_mul_f32 v[68:69], v[68:69], s[56:57] op_sel_hi:[1,0]
	v_pk_mul_f32 v[66:67], v[66:67], s[56:57] op_sel_hi:[1,0]
	v_pk_mul_f32 v[64:65], v[64:65], s[56:57] op_sel_hi:[1,0]
	v_cvt_pk_bf16_f32 v72, v68, v69
	v_cvt_pk_bf16_f32 v73, v70, v71
	v_lshl_add_u64 v[76:77], v[84:85], 0, v[144:145]
	v_cvt_pk_bf16_f32 v74, v64, v65
	v_cvt_pk_bf16_f32 v75, v66, v67
	global_store_dwordx4 v[76:77], v[72:75], off offset:256
	s_and_saveexec_b64 s[68:69], s[8:9]
	s_cbranch_execz .LBB0_232
	v_lshl_add_u64 v[72:73], s[44:45], 0, v[80:81]
	v_lshlrev_b32_e32 v144, 2, v158
	v_lshl_add_u64 v[74:75], v[72:73], 0, v[144:145]
	v_lshl_add_u64 v[72:73], v[74:75], 0, s[58:59]
	s_or_b64 s[10:11], s[10:11], exec
	global_store_dwordx4 v[74:75], v[68:71], off offset:512

.LBB0_235:
	s_or_b64 exec, exec, s[66:67]
	v_cmp_gt_i32_e32 vcc, s87, v156
	s_and_saveexec_b64 s[66:67], vcc
	s_cbranch_execz .LBB0_252
	v_add_u32_e32 v68, 0x80, v156
	v_ashrrev_i32_e32 v69, 31, v68
	s_movk_i32 s8, 0x3f80
	v_add_u32_e32 v144, 0xffffc080, v156
	v_lshlrev_b64 v[66:67], 9, v[68:69]
	v_cmp_gt_i32_e64 s[10:11], s8, v156
	v_lshlrev_b64 v[64:65], 11, v[144:145]
	s_and_b64 vcc, exec, s[6:7]
	v_cmp_lt_i32_e64 s[8:9], s31, v156
	s_cbranch_vccnz .LBB0_238
	s_and_b64 s[68:69], s[64:65], exec
	s_cselect_b32 s25, s89, s91
	s_cselect_b32 s68, s88, s90
	v_mov_b32_e32 v74, s68
	v_mov_b32_e32 v75, s25
	s_lshl_b32 s25, s24, 2
	v_lshl_add_u64 v[74:75], v[66:67], 1, v[74:75]
	v_lshlrev_b32_e32 v144, 1, v158
	s_add_u32 s68, s16, s25
	v_cvt_pk_bf16_f32 v70, v60, v61
	v_cvt_pk_bf16_f32 v71, v62, v63
	v_lshl_add_u64 v[74:75], v[74:75], 0, v[144:145]
	s_addc_u32 s69, s17, 0
	s_lshl_b32 s25, s72, 2
	v_cvt_pk_bf16_f32 v72, v56, v57
	v_cvt_pk_bf16_f32 v73, v58, v59
	global_store_dwordx4 v[74:75], v[70:73], off
	v_lshlrev_b32_e32 v144, 2, v158
	s_nop 0
	v_lshl_add_u64 v[70:71], v[66:67], 2, s[68:69]
	s_add_u32 s68, s16, s25
	s_addc_u32 s69, s17, 0
	v_lshl_add_u64 v[72:73], s[68:69], 0, v[64:65]
	v_cndmask_b32_e64 v71, v73, v71, s[10:11]
	v_cndmask_b32_e64 v70, v72, v70, s[10:11]
	v_lshl_add_u64 v[70:71], v[70:71], 0, v[144:145]
	s_mov_b64 s[68:69], -1
	global_store_dwordx4 v[70:71], v[60:63], off
	v_lshlrev_b64 v[68:69], 10, v[68:69]
	v_lshl_add_u64 v[68:69], s[40:41], 0, v[68:69]
	s_cbranch_execz .LBB0_239
	s_branch .LBB0_242

.LBB0_239:
	v_lshlrev_b32_e32 v144, 1, v158
	v_pk_mul_f32 v[62:63], v[62:63], s[56:57] op_sel_hi:[1,0]
	v_pk_mul_f32 v[60:61], v[60:61], s[56:57] op_sel_hi:[1,0]
	v_pk_mul_f32 v[58:59], v[58:59], s[56:57] op_sel_hi:[1,0]
	v_pk_mul_f32 v[56:57], v[56:57], s[56:57] op_sel_hi:[1,0]
	v_cvt_pk_bf16_f32 v70, v60, v61
	v_cvt_pk_bf16_f32 v71, v62, v63
	v_lshl_add_u64 v[74:75], v[68:69], 0, v[144:145]
	v_cvt_pk_bf16_f32 v72, v56, v57
	v_cvt_pk_bf16_f32 v73, v58, v59
	global_store_dwordx4 v[74:75], v[70:73], off
	s_and_saveexec_b64 s[70:71], s[8:9]
	s_cbranch_execz .LBB0_241
	v_lshl_add_u64 v[70:71], s[44:45], 0, v[64:65]
	v_lshlrev_b32_e32 v144, 2, v158
	v_lshl_add_u64 v[70:71], v[70:71], 0, v[144:145]
	s_or_b64 s[68:69], s[68:69], exec
	global_store_dwordx4 v[70:71], v[60:63], off

.LBB0_244:
	s_and_b64 s[68:69], s[64:65], exec
	s_cselect_b32 s25, s89, s91
	s_cselect_b32 s68, s88, s90
	v_mov_b32_e32 v60, s68
	v_mov_b32_e32 v61, s25
	s_lshl_b32 s25, s24, 2
	v_lshl_add_u64 v[60:61], v[66:67], 1, v[60:61]
	v_lshlrev_b32_e32 v144, 1, v158
	s_add_u32 s68, s16, s25
	v_cvt_pk_bf16_f32 v56, v52, v53
	v_cvt_pk_bf16_f32 v57, v54, v55
	v_lshl_add_u64 v[60:61], v[60:61], 0, v[144:145]
	s_addc_u32 s69, s17, 0
	s_lshl_b32 s25, s72, 2
	v_cvt_pk_bf16_f32 v58, v48, v49
	v_cvt_pk_bf16_f32 v59, v50, v51
	global_store_dwordx4 v[60:61], v[56:59], off offset:256
	v_lshlrev_b32_e32 v144, 2, v158
	s_nop 0
	v_lshl_add_u64 v[56:57], v[66:67], 2, s[68:69]
	s_add_u32 s68, s16, s25
	s_addc_u32 s69, s17, 0
	v_lshl_add_u64 v[58:59], s[68:69], 0, v[64:65]
	v_cndmask_b32_e64 v57, v59, v57, s[10:11]
	v_cndmask_b32_e64 v56, v58, v56, s[10:11]
	v_lshl_add_u64 v[58:59], v[56:57], 0, v[144:145]
	v_lshl_add_u64 v[56:57], v[58:59], 0, s[58:59]
	s_mov_b64 s[10:11], -1
	global_store_dwordx4 v[58:59], v[52:55], off offset:512
	s_cbranch_execz .LBB0_247
	s_branch .LBB0_250

.LBB0_247:
	v_lshlrev_b32_e32 v144, 1, v158
	v_pk_mul_f32 v[54:55], v[54:55], s[56:57] op_sel_hi:[1,0]
	v_pk_mul_f32 v[52:53], v[52:53], s[56:57] op_sel_hi:[1,0]
	v_pk_mul_f32 v[50:51], v[50:51], s[56:57] op_sel_hi:[1,0]
	v_pk_mul_f32 v[48:49], v[48:49], s[56:57] op_sel_hi:[1,0]
	v_cvt_pk_bf16_f32 v56, v52, v53
	v_cvt_pk_bf16_f32 v57, v54, v55
	v_lshl_add_u64 v[60:61], v[68:69], 0, v[144:145]
	v_cvt_pk_bf16_f32 v58, v48, v49
	v_cvt_pk_bf16_f32 v59, v50, v51
	global_store_dwordx4 v[60:61], v[56:59], off offset:256
	s_and_saveexec_b64 s[68:69], s[8:9]
	s_cbranch_execz .LBB0_249
	v_lshl_add_u64 v[56:57], s[44:45], 0, v[64:65]
	v_lshlrev_b32_e32 v144, 2, v158
	v_lshl_add_u64 v[58:59], v[56:57], 0, v[144:145]
	v_lshl_add_u64 v[56:57], v[58:59], 0, s[58:59]
	s_or_b64 s[10:11], s[10:11], exec
	global_store_dwordx4 v[58:59], v[52:55], off offset:512

.LBB0_252:
	s_or_b64 exec, exec, s[66:67]
	v_cmp_gt_i32_e32 vcc, s26, v156
	s_and_saveexec_b64 s[66:67], vcc
	s_cbranch_execz .LBB0_269
	v_add_u32_e32 v52, 0x90, v156
	v_ashrrev_i32_e32 v53, 31, v52
	s_movk_i32 s8, 0x3f70
	v_add_u32_e32 v144, 0xffffc090, v156
	v_lshlrev_b64 v[50:51], 9, v[52:53]
	v_cmp_gt_i32_e64 s[10:11], s8, v156
	v_lshlrev_b64 v[48:49], 11, v[144:145]
	s_and_b64 vcc, exec, s[6:7]
	v_cmp_lt_i32_e64 s[8:9], s27, v156
	s_cbranch_vccnz .LBB0_255
	s_and_b64 s[68:69], s[64:65], exec
	s_cselect_b32 s25, s89, s91
	s_cselect_b32 s68, s88, s90
	v_mov_b32_e32 v58, s68
	v_mov_b32_e32 v59, s25
	s_lshl_b32 s25, s24, 2
	v_lshl_add_u64 v[58:59], v[50:51], 1, v[58:59]
	v_lshlrev_b32_e32 v144, 1, v158
	s_add_u32 s68, s16, s25
	v_cvt_pk_bf16_f32 v54, v44, v45
	v_cvt_pk_bf16_f32 v55, v46, v47
	v_lshl_add_u64 v[58:59], v[58:59], 0, v[144:145]
	s_addc_u32 s69, s17, 0
	s_lshl_b32 s25, s72, 2
	v_cvt_pk_bf16_f32 v56, v40, v41
	v_cvt_pk_bf16_f32 v57, v42, v43
	global_store_dwordx4 v[58:59], v[54:57], off
	v_lshlrev_b32_e32 v144, 2, v158
	s_nop 0
	v_lshl_add_u64 v[54:55], v[50:51], 2, s[68:69]
	s_add_u32 s68, s16, s25
	s_addc_u32 s69, s17, 0
	v_lshl_add_u64 v[56:57], s[68:69], 0, v[48:49]
	v_cndmask_b32_e64 v55, v57, v55, s[10:11]
	v_cndmask_b32_e64 v54, v56, v54, s[10:11]
	v_lshl_add_u64 v[54:55], v[54:55], 0, v[144:145]
	s_mov_b64 s[68:69], -1
	global_store_dwordx4 v[54:55], v[44:47], off
	v_lshlrev_b64 v[52:53], 10, v[52:53]
	v_lshl_add_u64 v[52:53], s[40:41], 0, v[52:53]
	s_cbranch_execz .LBB0_256
	s_branch .LBB0_259

.LBB0_256:
	v_lshlrev_b32_e32 v144, 1, v158
	v_pk_mul_f32 v[46:47], v[46:47], s[56:57] op_sel_hi:[1,0]
	v_pk_mul_f32 v[44:45], v[44:45], s[56:57] op_sel_hi:[1,0]
	v_pk_mul_f32 v[42:43], v[42:43], s[56:57] op_sel_hi:[1,0]
	v_pk_mul_f32 v[40:41], v[40:41], s[56:57] op_sel_hi:[1,0]
	v_cvt_pk_bf16_f32 v54, v44, v45
	v_cvt_pk_bf16_f32 v55, v46, v47
	v_lshl_add_u64 v[58:59], v[52:53], 0, v[144:145]
	v_cvt_pk_bf16_f32 v56, v40, v41
	v_cvt_pk_bf16_f32 v57, v42, v43
	global_store_dwordx4 v[58:59], v[54:57], off
	s_and_saveexec_b64 s[70:71], s[8:9]
	s_cbranch_execz .LBB0_258
	v_lshl_add_u64 v[54:55], s[44:45], 0, v[48:49]
	v_lshlrev_b32_e32 v144, 2, v158
	v_lshl_add_u64 v[54:55], v[54:55], 0, v[144:145]
	s_or_b64 s[68:69], s[68:69], exec
	global_store_dwordx4 v[54:55], v[44:47], off

.LBB0_261:
	s_and_b64 s[68:69], s[64:65], exec
	s_cselect_b32 s25, s89, s91
	s_cselect_b32 s68, s88, s90
	v_mov_b32_e32 v44, s68
	v_mov_b32_e32 v45, s25
	s_lshl_b32 s25, s24, 2
	v_lshl_add_u64 v[44:45], v[50:51], 1, v[44:45]
	v_lshlrev_b32_e32 v144, 1, v158
	s_add_u32 s68, s16, s25
	v_cvt_pk_bf16_f32 v40, v36, v37
	v_cvt_pk_bf16_f32 v41, v38, v39
	v_lshl_add_u64 v[44:45], v[44:45], 0, v[144:145]
	s_addc_u32 s69, s17, 0
	s_lshl_b32 s25, s72, 2
	v_cvt_pk_bf16_f32 v42, v32, v33
	v_cvt_pk_bf16_f32 v43, v34, v35
	global_store_dwordx4 v[44:45], v[40:43], off offset:256
	v_lshlrev_b32_e32 v144, 2, v158
	s_nop 0
	v_lshl_add_u64 v[40:41], v[50:51], 2, s[68:69]
	s_add_u32 s68, s16, s25
	s_addc_u32 s69, s17, 0
	v_lshl_add_u64 v[42:43], s[68:69], 0, v[48:49]
	v_cndmask_b32_e64 v41, v43, v41, s[10:11]
	v_cndmask_b32_e64 v40, v42, v40, s[10:11]
	v_lshl_add_u64 v[42:43], v[40:41], 0, v[144:145]
	v_lshl_add_u64 v[40:41], v[42:43], 0, s[58:59]
	s_mov_b64 s[10:11], -1
	global_store_dwordx4 v[42:43], v[36:39], off offset:512
	s_cbranch_execz .LBB0_264
	s_branch .LBB0_267

.LBB0_264:
	v_lshlrev_b32_e32 v144, 1, v158
	v_pk_mul_f32 v[38:39], v[38:39], s[56:57] op_sel_hi:[1,0]
	v_pk_mul_f32 v[36:37], v[36:37], s[56:57] op_sel_hi:[1,0]
	v_pk_mul_f32 v[34:35], v[34:35], s[56:57] op_sel_hi:[1,0]
	v_pk_mul_f32 v[32:33], v[32:33], s[56:57] op_sel_hi:[1,0]
	v_cvt_pk_bf16_f32 v40, v36, v37
	v_cvt_pk_bf16_f32 v41, v38, v39
	v_lshl_add_u64 v[44:45], v[52:53], 0, v[144:145]
	v_cvt_pk_bf16_f32 v42, v32, v33
	v_cvt_pk_bf16_f32 v43, v34, v35
	global_store_dwordx4 v[44:45], v[40:43], off offset:256
	s_and_saveexec_b64 s[68:69], s[8:9]
	s_cbranch_execz .LBB0_266
	v_lshl_add_u64 v[40:41], s[44:45], 0, v[48:49]
	v_lshlrev_b32_e32 v144, 2, v158
	v_lshl_add_u64 v[42:43], v[40:41], 0, v[144:145]
	v_lshl_add_u64 v[40:41], v[42:43], 0, s[58:59]
	s_or_b64 s[10:11], s[10:11], exec
	global_store_dwordx4 v[42:43], v[36:39], off offset:512

.LBB0_269:
	s_or_b64 exec, exec, s[66:67]
	v_cmp_gt_i32_e32 vcc, s14, v156
	s_and_saveexec_b64 s[66:67], vcc
	s_cbranch_execz .LBB0_286
	v_add_u32_e32 v36, 0xa0, v156
	v_ashrrev_i32_e32 v37, 31, v36
	s_movk_i32 s8, 0x3f60
	v_add_u32_e32 v144, 0xffffc0a0, v156
	v_lshlrev_b64 v[34:35], 9, v[36:37]
	v_cmp_gt_i32_e64 s[10:11], s8, v156
	v_lshlrev_b64 v[32:33], 11, v[144:145]
	s_and_b64 vcc, exec, s[6:7]
	v_cmp_lt_i32_e64 s[8:9], s15, v156
	s_cbranch_vccnz .LBB0_272
	s_and_b64 s[68:69], s[64:65], exec
	s_cselect_b32 s25, s89, s91
	s_cselect_b32 s68, s88, s90
	v_mov_b32_e32 v42, s68
	v_mov_b32_e32 v43, s25
	s_lshl_b32 s25, s24, 2
	v_lshl_add_u64 v[42:43], v[34:35], 1, v[42:43]
	v_lshlrev_b32_e32 v144, 1, v158
	s_add_u32 s68, s16, s25
	v_cvt_pk_bf16_f32 v38, v28, v29
	v_cvt_pk_bf16_f32 v39, v30, v31
	v_lshl_add_u64 v[42:43], v[42:43], 0, v[144:145]
	s_addc_u32 s69, s17, 0
	s_lshl_b32 s25, s72, 2
	v_cvt_pk_bf16_f32 v40, v24, v25
	v_cvt_pk_bf16_f32 v41, v26, v27
	global_store_dwordx4 v[42:43], v[38:41], off
	v_lshlrev_b32_e32 v144, 2, v158
	s_nop 0
	v_lshl_add_u64 v[38:39], v[34:35], 2, s[68:69]
	s_add_u32 s68, s16, s25
	s_addc_u32 s69, s17, 0
	v_lshl_add_u64 v[40:41], s[68:69], 0, v[32:33]
	v_cndmask_b32_e64 v39, v41, v39, s[10:11]
	v_cndmask_b32_e64 v38, v40, v38, s[10:11]
	v_lshl_add_u64 v[38:39], v[38:39], 0, v[144:145]
	s_mov_b64 s[68:69], -1
	global_store_dwordx4 v[38:39], v[28:31], off
	v_lshlrev_b64 v[36:37], 10, v[36:37]
	v_lshl_add_u64 v[36:37], s[40:41], 0, v[36:37]
	s_cbranch_execz .LBB0_273
	s_branch .LBB0_276

.LBB0_273:
	v_lshlrev_b32_e32 v144, 1, v158
	v_pk_mul_f32 v[30:31], v[30:31], s[56:57] op_sel_hi:[1,0]
	v_pk_mul_f32 v[28:29], v[28:29], s[56:57] op_sel_hi:[1,0]
	v_pk_mul_f32 v[26:27], v[26:27], s[56:57] op_sel_hi:[1,0]
	v_pk_mul_f32 v[24:25], v[24:25], s[56:57] op_sel_hi:[1,0]
	v_cvt_pk_bf16_f32 v38, v28, v29
	v_cvt_pk_bf16_f32 v39, v30, v31
	v_lshl_add_u64 v[42:43], v[36:37], 0, v[144:145]
	v_cvt_pk_bf16_f32 v40, v24, v25
	v_cvt_pk_bf16_f32 v41, v26, v27
	global_store_dwordx4 v[42:43], v[38:41], off
	s_and_saveexec_b64 s[70:71], s[8:9]
	s_cbranch_execz .LBB0_275
	v_lshl_add_u64 v[38:39], s[44:45], 0, v[32:33]
	v_lshlrev_b32_e32 v144, 2, v158
	v_lshl_add_u64 v[38:39], v[38:39], 0, v[144:145]
	s_or_b64 s[68:69], s[68:69], exec
	global_store_dwordx4 v[38:39], v[28:31], off

.LBB0_278:
	s_and_b64 s[68:69], s[64:65], exec
	s_cselect_b32 s25, s89, s91
	s_cselect_b32 s68, s88, s90
	v_mov_b32_e32 v28, s68
	v_mov_b32_e32 v29, s25
	s_lshl_b32 s25, s24, 2
	v_lshl_add_u64 v[28:29], v[34:35], 1, v[28:29]
	v_lshlrev_b32_e32 v144, 1, v158
	s_add_u32 s68, s16, s25
	v_cvt_pk_bf16_f32 v24, v20, v21
	v_cvt_pk_bf16_f32 v25, v22, v23
	v_lshl_add_u64 v[28:29], v[28:29], 0, v[144:145]
	s_addc_u32 s69, s17, 0
	s_lshl_b32 s25, s72, 2
	v_cvt_pk_bf16_f32 v26, v16, v17
	v_cvt_pk_bf16_f32 v27, v18, v19
	global_store_dwordx4 v[28:29], v[24:27], off offset:256
	v_lshlrev_b32_e32 v144, 2, v158
	s_nop 0
	v_lshl_add_u64 v[24:25], v[34:35], 2, s[68:69]
	s_add_u32 s68, s16, s25
	s_addc_u32 s69, s17, 0
	v_lshl_add_u64 v[26:27], s[68:69], 0, v[32:33]
	v_cndmask_b32_e64 v25, v27, v25, s[10:11]
	v_cndmask_b32_e64 v24, v26, v24, s[10:11]
	v_lshl_add_u64 v[26:27], v[24:25], 0, v[144:145]
	v_lshl_add_u64 v[24:25], v[26:27], 0, s[58:59]
	s_mov_b64 s[10:11], -1
	global_store_dwordx4 v[26:27], v[20:23], off offset:512
	s_cbranch_execz .LBB0_281
	s_branch .LBB0_284

.LBB0_281:
	v_lshlrev_b32_e32 v144, 1, v158
	v_pk_mul_f32 v[22:23], v[22:23], s[56:57] op_sel_hi:[1,0]
	v_pk_mul_f32 v[20:21], v[20:21], s[56:57] op_sel_hi:[1,0]
	v_pk_mul_f32 v[18:19], v[18:19], s[56:57] op_sel_hi:[1,0]
	v_pk_mul_f32 v[16:17], v[16:17], s[56:57] op_sel_hi:[1,0]
	v_cvt_pk_bf16_f32 v24, v20, v21
	v_cvt_pk_bf16_f32 v25, v22, v23
	v_lshl_add_u64 v[28:29], v[36:37], 0, v[144:145]
	v_cvt_pk_bf16_f32 v26, v16, v17
	v_cvt_pk_bf16_f32 v27, v18, v19
	global_store_dwordx4 v[28:29], v[24:27], off offset:256
	s_and_saveexec_b64 s[68:69], s[8:9]
	s_cbranch_execz .LBB0_283
	v_lshl_add_u64 v[24:25], s[44:45], 0, v[32:33]
	v_lshlrev_b32_e32 v144, 2, v158
	v_lshl_add_u64 v[26:27], v[24:25], 0, v[144:145]
	v_lshl_add_u64 v[24:25], v[26:27], 0, s[58:59]
	s_or_b64 s[10:11], s[10:11], exec
	global_store_dwordx4 v[26:27], v[20:23], off offset:512

.LBB0_286:
	s_or_b64 exec, exec, s[66:67]
	v_cmp_gt_i32_e32 vcc, s81, v156
	s_and_saveexec_b64 s[66:67], vcc
	s_cbranch_execz .LBB0_303
	v_add_u32_e32 v22, 0xb0, v156
	v_ashrrev_i32_e32 v23, 31, v22
	s_movk_i32 s8, 0x3f50
	v_add_u32_e32 v144, 0xffffc0b0, v156
	v_lshlrev_b64 v[20:21], 9, v[22:23]
	v_cmp_gt_i32_e64 s[10:11], s8, v156
	v_lshlrev_b64 v[16:17], 11, v[144:145]
	v_cmp_lt_i32_e64 s[8:9], s80, v156
	s_and_b64 vcc, exec, s[6:7]
	v_lshlrev_b32_e32 v144, 1, v158
	v_lshlrev_b32_e32 v18, 2, v158
	s_cbranch_vccnz .LBB0_289
	s_and_b64 s[68:69], s[64:65], exec
	s_cselect_b32 s25, s89, s91
	s_cselect_b32 s68, s88, s90
	v_mov_b32_e32 v28, s68
	v_mov_b32_e32 v29, s25
	s_lshl_b32 s25, s24, 2
	v_lshl_add_u64 v[28:29], v[20:21], 1, v[28:29]
	s_add_u32 s68, s16, s25
	v_cvt_pk_bf16_f32 v24, v12, v13
	v_cvt_pk_bf16_f32 v25, v14, v15
	v_lshl_add_u64 v[28:29], v[28:29], 0, v[144:145]
	s_addc_u32 s69, s17, 0
	s_lshl_b32 s25, s72, 2
	v_cvt_pk_bf16_f32 v26, v8, v9
	v_cvt_pk_bf16_f32 v27, v10, v11
	global_store_dwordx4 v[28:29], v[24:27], off
	v_mov_b32_e32 v19, v145
	s_nop 0
	v_lshl_add_u64 v[24:25], v[20:21], 2, s[68:69]
	s_add_u32 s68, s16, s25
	s_addc_u32 s69, s17, 0
	v_lshl_add_u64 v[26:27], s[68:69], 0, v[16:17]
	v_cndmask_b32_e64 v25, v27, v25, s[10:11]
	v_cndmask_b32_e64 v24, v26, v24, s[10:11]
	v_lshl_add_u64 v[24:25], v[24:25], 0, v[18:19]
	s_mov_b64 s[68:69], -1
	global_store_dwordx4 v[24:25], v[12:15], off
	v_lshlrev_b64 v[22:23], 10, v[22:23]
	v_lshl_add_u64 v[22:23], s[40:41], 0, v[22:23]
	s_cbranch_execz .LBB0_290
	s_branch .LBB0_293

.LBB0_290:
	v_pk_mul_f32 v[14:15], v[14:15], s[56:57] op_sel_hi:[1,0]
	v_pk_mul_f32 v[12:13], v[12:13], s[56:57] op_sel_hi:[1,0]
	v_pk_mul_f32 v[10:11], v[10:11], s[56:57] op_sel_hi:[1,0]
	v_pk_mul_f32 v[8:9], v[8:9], s[56:57] op_sel_hi:[1,0]
	v_cvt_pk_bf16_f32 v24, v12, v13
	v_cvt_pk_bf16_f32 v25, v14, v15
	v_lshl_add_u64 v[28:29], v[22:23], 0, v[144:145]
	v_cvt_pk_bf16_f32 v26, v8, v9
	v_cvt_pk_bf16_f32 v27, v10, v11
	global_store_dwordx4 v[28:29], v[24:27], off
	s_and_saveexec_b64 s[70:71], s[8:9]
	s_cbranch_execz .LBB0_292
	v_lshl_add_u64 v[24:25], s[44:45], 0, v[16:17]
	v_mov_b32_e32 v19, v145
	v_lshl_add_u64 v[24:25], v[24:25], 0, v[18:19]
	s_or_b64 s[68:69], s[68:69], exec
	global_store_dwordx4 v[24:25], v[12:15], off

.LBB0_295:
	s_and_b64 s[6:7], s[64:65], exec
	s_cselect_b32 s6, s89, s91
	s_cselect_b32 s7, s88, s90
	v_mov_b32_e32 v12, s7
	v_mov_b32_e32 v13, s6
	s_lshl_b32 s6, s24, 2
	v_lshl_add_u64 v[12:13], v[20:21], 1, v[12:13]
	s_add_u32 s6, s16, s6
	v_cvt_pk_bf16_f32 v8, v4, v5
	v_cvt_pk_bf16_f32 v9, v6, v7
	v_lshl_add_u64 v[12:13], v[12:13], 0, v[144:145]
	s_addc_u32 s7, s17, 0
	v_cvt_pk_bf16_f32 v10, v0, v1
	v_cvt_pk_bf16_f32 v11, v2, v3
	global_store_dwordx4 v[12:13], v[8:11], off offset:256
	v_mov_b32_e32 v19, v145
	s_nop 0
	v_lshl_add_u64 v[8:9], v[20:21], 2, s[6:7]
	s_lshl_b32 s6, s72, 2
	s_add_u32 s6, s16, s6
	s_addc_u32 s7, s17, 0
	v_lshl_add_u64 v[10:11], s[6:7], 0, v[16:17]
	v_cndmask_b32_e64 v9, v11, v9, s[10:11]
	v_cndmask_b32_e64 v8, v10, v8, s[10:11]
	v_lshl_add_u64 v[10:11], v[8:9], 0, v[18:19]
	v_lshl_add_u64 v[8:9], v[10:11], 0, s[58:59]
	s_mov_b64 s[6:7], -1
	global_store_dwordx4 v[10:11], v[4:7], off offset:512
	s_cbranch_execz .LBB0_300
	s_and_b64 exec, exec, s[6:7]
	s_cbranch_execz .LBB0_303

.LBB0_300:
	s_nop 0
	v_pk_mul_f32 v[6:7], v[6:7], s[56:57] op_sel_hi:[1,0]
	v_pk_mul_f32 v[4:5], v[4:5], s[56:57] op_sel_hi:[1,0]
	v_pk_mul_f32 v[2:3], v[2:3], s[56:57] op_sel_hi:[1,0]
	v_pk_mul_f32 v[0:1], v[0:1], s[56:57] op_sel_hi:[1,0]
	v_cvt_pk_bf16_f32 v8, v4, v5
	v_cvt_pk_bf16_f32 v9, v6, v7
	v_lshl_add_u64 v[12:13], v[22:23], 0, v[144:145]
	v_cvt_pk_bf16_f32 v10, v0, v1
	v_cvt_pk_bf16_f32 v11, v2, v3
	global_store_dwordx4 v[12:13], v[8:11], off offset:256
	s_and_saveexec_b64 s[10:11], s[8:9]
	s_cbranch_execz .LBB0_302
	v_lshl_add_u64 v[8:9], s[44:45], 0, v[16:17]
	v_mov_b32_e32 v19, v145
	v_lshl_add_u64 v[10:11], v[8:9], 0, v[18:19]
	v_lshl_add_u64 v[8:9], v[10:11], 0, s[58:59]
	s_or_b64 s[6:7], s[6:7], exec
	global_store_dwordx4 v[10:11], v[4:7], off offset:512
